# phase 2: XCD groups start the q/k GEMM staggered by 0/3/6/9 us so the epilogue store bursts of different XCDs do not coincide
# speedup vs baseline: 1.0125x; 1.0125x over previous
.LBB0_174:
	s_cmp_lt_i32 s24, 3
	s_cselect_b64 s[12:13], -1, 0
	s_and_b64 s[4:5], s[12:13], s[4:5]
	s_andn2_b64 vcc, exec, s[4:5]
	s_cbranch_vccnz .LBB0_207
	s_and_b32 s98, s2, 3
	s_cmp_eq_u32 s98, 0
	s_cbranch_scc1 .Lp2_go
.Lp2_dly:
	s_sleep 100
	s_add_i32 s98, s98, -1
	s_cmp_lg_u32 s98, 0
	s_cbranch_scc1 .Lp2_dly
.Lp2_go:
	s_mov_b64 s[4:5], s[0:1]
	s_mov_b32 s6, 0
	s_and_b32 s55, s33, 0xffffffc0
	v_mbcnt_lo_u32_b32 v0, -1, s6
	v_mbcnt_hi_u32_b32 v0, -1, v0
	v_or_b32_e32 v8, s55, v0
	s_load_dword s54, s[0:1], 0xb8
	s_mov_b32 s56, 0
	s_cmpk_gt_i32 s2, 0x5ff
	v_readfirstlane_b32 s21, v8
	s_cbranch_scc1 .LBB0_191
	s_load_dwordx2 s[14:15], s[4:5], 0xa0
	v_lshlrev_b32_e32 v0, 4, v8
	v_and_b32_e32 v1, 32, v8
	v_bitop3_b32 v0, v0, v1, 48 bitop3:0x6c
	v_lshrrev_b32_e32 v1, 1, v8
	v_and_b32_e32 v128, 24, v1
	v_lshrrev_b32_e32 v1, 5, v8
	s_waitcnt lgkmcnt(0)
	s_add_u32 s57, s14, 0xe800000
	v_and_b32_e32 v1, 4, v1
	v_bfe_u32 v3, v8, 2, 2
	v_bfe_u32 v2, v8, 2, 4
	s_addc_u32 s58, s15, 0
	v_or3_b32 v1, v1, v3, v128
	v_lshrrev_b32_e32 v3, 3, v8
	s_add_u32 s59, s14, 0xa00000
	v_and_or_b32 v4, v3, 48, v2
	v_and_or_b32 v5, v3, 32, v1
	v_or_b32_e32 v3, 64, v3
	s_movk_i32 s6, 0x70
	s_addc_u32 s63, s15, 0
	v_and_or_b32 v2, v3, s6, v2
	s_movk_i32 s6, 0x60
	s_ashr_i32 s65, s2, 31
	v_and_or_b32 v1, v3, s6, v1
	s_lshr_b32 s6, s65, 29
	s_add_i32 s6, s2, s6
	s_lshr_b32 s23, s21, 6
	s_ashr_i32 s7, s6, 3
	s_and_b32 s6, s6, -8
	s_lshr_b32 s22, s21, 8
	s_lshl_b32 s64, s23, 10
	s_sub_i32 s6, s2, s6
	s_cmp_lt_i32 s6, 0
	s_movk_i32 s66, 0xc1
	s_cselect_b32 s8, s66, 0xc0
	s_mul_i32 s6, s8, s6
	s_add_i32 s6, s6, s7
	s_ashr_i32 s7, s6, 31
	s_lshr_b32 s7, s7, 26
	s_add_i32 s7, s6, s7
	s_ashr_i32 s8, s7, 6
	s_andn2_b32 s7, s7, 63
	s_sub_i32 s6, s6, s7
	s_bfe_i32 s7, s6, 0x80000
	s_bfe_u32 s7, s7, 0x3000c
	s_add_i32 s7, s6, s7
	s_bfe_i32 s9, s7, 0x80000
	s_and_b32 s7, s7, 0xf8
	s_sext_i32_i16 s9, s9
	s_sub_i32 s6, s6, s7
	s_lshl_b32 s8, s8, 3
	s_lshr_b32 s20, s9, 3
	s_sext_i32_i8 s6, s6
	s_add_i32 s46, s8, s6
	s_bfe_i64 s[6:7], s[20:21], 0x100000
	s_lshl_b64 s[6:7], s[6:7], 18
	s_add_u32 s6, s59, s6
	s_addc_u32 s7, s63, s7
	s_ashr_i32 s47, s46, 31
	s_lshl_b64 s[8:9], s[46:47], 18
	s_add_u32 s48, s57, s8
	v_and_or_b32 v0, v8, 64, v0
	s_addc_u32 s49, s58, s9
	s_add_i32 s47, s64, 0
	v_lshl_or_b32 v132, v5, 10, v0
	s_add_i32 m0, s47, 0x10000
	v_lshl_or_b32 v136, v1, 10, v0
	global_load_lds_dwordx4 v132, s[6:7]
	s_add_i32 m0, s47, 0x12000
	s_add_u32 s8, s6, 0x20000
	global_load_lds_dwordx4 v136, s[6:7]
	s_addc_u32 s9, s7, 0
	s_add_i32 m0, s47, 0x14000
	s_add_i32 s67, s47, 0x2000
	global_load_lds_dwordx4 v132, s[8:9]
	s_add_i32 m0, s47, 0x16000
	v_lshl_or_b32 v130, v4, 10, v0
	global_load_lds_dwordx4 v136, s[8:9]
	s_mov_b32 m0, s47
	s_add_u32 s8, s48, 0x20000
	v_lshl_or_b32 v134, v2, 10, v0
	global_load_lds_dwordx4 v130, s[48:49]
	s_mov_b32 m0, s67
	s_addc_u32 s9, s49, 0
	s_add_i32 s68, s47, 0x4000
	global_load_lds_dwordx4 v134, s[48:49]
	s_mov_b32 m0, s68
	s_add_i32 s69, s47, 0x6000
	global_load_lds_dwordx4 v130, s[8:9]
	s_mov_b32 m0, s69
	v_mov_b32_e32 v133, 0
	global_load_lds_dwordx4 v134, s[8:9]
	s_load_dwordx4 s[8:11], s[4:5], 0x48
	v_mov_b32_e32 v137, v133
	v_mov_b32_e32 v131, v133
	v_mov_b32_e32 v135, v133
	s_cmp_eq_u32 s22, 1
	v_lshl_add_u64 v[6:7], s[6:7], 0, v[132:133]
	v_lshl_add_u64 v[4:5], s[6:7], 0, v[136:137]
	v_lshl_add_u64 v[0:1], s[48:49], 0, v[130:131]
	s_cselect_b64 s[18:19], -1, 0
	s_cmp_lg_u32 s22, 1
	v_lshl_add_u64 v[2:3], s[48:49], 0, v[134:135]
	s_cbranch_scc1 .LBB0_178
	s_barrier
